# attention phase hand-written: fixed-shift softmax bound folded into MFMA C, exp/sum/pack interleaved with MFMAs, epilogue loads hoisted
# speedup vs baseline: 1.0520x; 1.0520x over previous
.LBB0_19:
	s_load_dwordx16 s[52:67], s[0:1], 0x40
	s_waitcnt lgkmcnt(0)
	v_mbcnt_lo_u32_b32 v252, -1, 0
	v_mbcnt_hi_u32_b32 v252, -1, v252
	v_lshlrev_b32_e32 v252, 2, v252
	global_load_dword v253, v252, s[90:91]
	global_load_dword v254, v252, s[52:53]
	s_waitcnt vmcnt(0)
	v_mul_f32_e32 v253, v253, v254
	v_and_b32_e32 v253, 0x7fffffff, v253
	v_xor_b32_e32 v254, 4, v252
	ds_bpermute_b32 v255, v254, v253
	s_waitcnt lgkmcnt(0)
	v_max_f32_e32 v253, v253, v255
	v_xor_b32_e32 v254, 8, v252
	ds_bpermute_b32 v255, v254, v253
	s_waitcnt lgkmcnt(0)
	v_max_f32_e32 v253, v253, v255
	v_xor_b32_e32 v254, 16, v252
	ds_bpermute_b32 v255, v254, v253
	s_waitcnt lgkmcnt(0)
	v_max_f32_e32 v253, v253, v255
	v_xor_b32_e32 v254, 32, v252
	ds_bpermute_b32 v255, v254, v253
	s_waitcnt lgkmcnt(0)
	v_max_f32_e32 v253, v253, v255
	v_xor_b32_e32 v254, 64, v252
	ds_bpermute_b32 v255, v254, v253
	s_waitcnt lgkmcnt(0)
	v_max_f32_e32 v253, v253, v255
	v_xor_b32_e32 v254, 128, v252
	ds_bpermute_b32 v255, v254, v253
	s_waitcnt lgkmcnt(0)
	v_max_f32_e32 v253, v253, v255
	v_mul_f32_e32 v253, 0x4138aa3b, v253
	v_add_f32_e32 v246, 1.0, v253
	v_xor_b32_e32 v248, 0x80000000, v246
	v_mov_b32_e32 v249, v248
	v_mov_b32_e32 v250, v248
	v_mov_b32_e32 v251, v248
	s_and_b32 s0, s14, 0xffffffc0
	s_add_u32 s16, s92, 0x800000
	s_addc_u32 s17, s93, 0
	s_cmp_lt_i32 s94, 1
	s_cselect_b64 s[18:19], -1, 0
	s_cmp_gt_i32 s95, 0
	v_writelane_b32 v245, s0, 0
	s_cselect_b64 s[0:1], -1, 0
	s_and_b64 s[0:1], s[18:19], s[0:1]
	s_lshl_b32 s28, s22, 3
	s_add_u32 s4, s92, 0x2700000
	s_addc_u32 s5, s93, 0
	v_writelane_b32 v245, s4, 1
	v_mbcnt_lo_u32_b32 v192, -1, 0
	s_nop 0
	v_writelane_b32 v245, s5, 2
	s_add_u32 s4, s92, 0x1c00000
	s_addc_u32 s5, s93, 0
	v_writelane_b32 v245, s4, 3
	s_nop 1
	v_writelane_b32 v245, s5, 4
	s_add_u32 s4, s92, 0x1a00000
	s_addc_u32 s5, s93, 0
	v_writelane_b32 v245, s4, 5
	s_andn2_b64 vcc, exec, s[0:1]
	s_nop 0
	v_writelane_b32 v245, s5, 6
	v_writelane_b32 v245, s22, 7
	s_nop 1
	v_writelane_b32 v245, s23, 8
	s_cbranch_vccnz .LBB0_95
	v_mbcnt_hi_u32_b32 v36, -1, v192
	v_readlane_b32 s0, v245, 0
	s_lshl_b32 s3, s3, 3
	s_mov_b32 s5, 0
	v_add_u32_e32 v33, s0, v36
	s_nop 0
	v_readfirstlane_b32 s0, v33
	s_ashr_i32 s15, s0, 6
	v_and_b32_e32 v37, 63, v33
	s_add_i32 s24, s15, s3
	s_cmpk_gt_i32 s24, 0x247f
	v_lshlrev_b32_e32 v32, 3, v37
	s_cbranch_scc1 .LBB0_79
	s_waitcnt lgkmcnt(0)
	s_cmp_lg_u64 s[66:67], 0
	s_mul_i32 s0, s15, 0x2200
	s_cselect_b64 s[6:7], -1, 0
	s_add_i32 s0, s0, 0
	v_lshrrev_b32_e32 v38, 5, v37
	v_and_b32_e32 v16, 31, v33
	s_add_i32 s0, s0, 0x10000
	v_mul_u32_u24_e32 v0, 0x84, v38
	v_lshlrev_b32_e32 v14, 2, v16
	v_add3_u32 v39, s0, v0, v14
	v_lshrrev_b32_e32 v40, 3, v37
	v_and_b32_e32 v0, 56, v32
	v_mul_u32_u24_e32 v4, 0x84, v0
	v_lshlrev_b32_e32 v5, 2, v40
	v_add3_u32 v41, s0, v4, v5
	v_or_b32_e32 v4, 2, v38
	v_mul_u32_u24_e32 v4, 0x84, v4
	v_add3_u32 v45, s0, v4, v14
	v_readlane_b32 s0, v245, 3
	v_mov_b32_e32 v1, 0
	v_lshlrev_b32_e32 v0, 1, v0
	v_readlane_b32 s1, v245, 4
	v_readlane_b32 s8, v245, 1
	v_readlane_b32 s9, v245, 2
	v_lshl_add_u64 v[4:5], s[0:1], 0, v[0:1]
	v_readlane_b32 s0, v245, 5
	v_readlane_b32 s1, v245, 6
	v_mov_b32_e32 v15, v1
	v_lshl_add_u64 v[2:3], s[8:9], 0, v[0:1]
	v_lshl_add_u64 v[6:7], s[0:1], 0, v[0:1]
	s_lshl_b32 s0, s24, 5
	v_or_b32_e32 v42, 8, v40
	v_or_b32_e32 v43, 16, v40
	v_or_b32_e32 v44, 24, v40
	v_add_u32_e32 v46, 0x108, v45
	v_add_u32_e32 v47, 0x210, v45
	v_add_u32_e32 v48, 0x318, v45
	v_add_u32_e32 v49, 0x420, v45
	v_add_u32_e32 v50, 0x528, v45
	v_add_u32_e32 v51, 0x630, v45
	v_add_u32_e32 v52, 0x738, v45
	v_add_u32_e32 v53, 0x840, v45
	v_add_u32_e32 v54, 0x948, v45
	v_add_u32_e32 v55, 0xa50, v45
	v_add_u32_e32 v56, 0xb58, v45
	v_add_u32_e32 v57, 0xc60, v45
	v_add_u32_e32 v58, 0xd68, v45
	v_add_u32_e32 v59, 0xe70, v45
	v_add_u32_e32 v60, 0xf78, v45
	v_add_u32_e32 v61, 0x1080, v45
	v_add_u32_e32 v62, 0x1188, v45
	v_add_u32_e32 v63, 0x1290, v45
	v_add_u32_e32 v64, 0x1398, v45
	v_add_u32_e32 v65, 0x14a0, v45
	v_add_u32_e32 v66, 0x15a8, v45
	v_add_u32_e32 v67, 0x16b0, v45
	v_add_u32_e32 v68, 0x17b8, v45
	v_add_u32_e32 v69, 0x18c0, v45
	v_add_u32_e32 v70, 0x19c8, v45
	v_add_u32_e32 v71, 0x1ad0, v45
	v_add_u32_e32 v72, 0x1bd8, v45
	v_add_u32_e32 v73, 0x1ce0, v45
	v_add_u32_e32 v74, 0x1de8, v45
	v_add_u32_e32 v75, 0x1ef0, v45
	v_lshl_add_u64 v[8:9], s[16:17], 0, v[0:1]
	v_lshl_add_u64 v[10:11], s[72:73], 0, v[14:15]
	v_lshl_add_u64 v[12:13], s[64:65], 0, v[14:15]
	v_lshl_add_u64 v[14:15], s[80:81], 0, v[14:15]
	s_add_i32 s10, s0, 0xfffff810
	s_lshl_b32 s11, s28, 5
	s_lshl_b32 s12, s24, 6
	s_lshl_b32 s13, s28, 6
	s_lshl_b32 s20, s24, 1
	s_lshl_b32 s21, s28, 1
	v_lshlrev_b32_e32 v0, 2, v16
	s_mov_b32 s22, 0x2c000
	s_mov_b32 s23, 0x31000
	s_mov_b32 s25, 0x37000
	s_mov_b32 s26, 0x3c000
	s_mov_b32 s27, 0x42000
	s_mov_b32 s29, 0x47000
	s_mov_b32 s30, 0x4d000
	s_mov_b32 s31, 0x52000
	s_mov_b32 s34, 0x58000
	s_mov_b32 s35, 0x5d000
	s_mov_b32 s36, 0x63000
	s_mov_b32 s37, 0x68000
	s_mov_b32 s38, 0x6e000
	s_mov_b32 s39, 0x73000
	s_mov_b32 s40, 0x79000
	s_mov_b32 s41, 0x7e000
	s_mov_b32 s42, 0x84000
	s_mov_b32 s43, 0x89000
	s_mov_b32 s44, 0x8f000
	s_mov_b32 s45, 0x94000
	s_mov_b32 s46, 0x9a000
	s_movk_i32 s47, 0x1010
	s_mov_b32 s48, 0x9040
	s_mov_b32 s49, s24
	s_branch .LBB0_25

.Lattn_main:
	v_writelane_b32 v244, s79, 16
	v_mov_b32_e32 v203, v97
	v_mbcnt_hi_u32_b32 v204, -1, v192
	v_readlane_b32 s4, v245, 0
	v_readlane_b32 s0, v245, 7
	s_lshr_b32 s6, s4, 6
	s_mov_b32 s4, s62
	s_mov_b32 s5, s63
	s_cmp_eq_u32 s0, 0x100
	s_cselect_b32 s7, 1, 0
	s_mov_b32 s78, s0
	s_add_u32 s8, s92, 0x6d00000
	s_addc_u32 s9, s93, 0
	s_add_u32 s10, s92, 0x8d00000
	s_addc_u32 s11, s93, 0
	s_add_u32 s12, s92, 0xad00000
	s_addc_u32 s13, s93, 0
	s_add_u32 s14, s92, 0x4d00000
	s_addc_u32 s15, s93, 0
	s_add_u32 s16, s92, 0xcd00000
	s_addc_u32 s17, s93, 0
	s_add_u32 s18, s74, 0x2000000
	s_addc_u32 s19, s75, 0
	v_and_b32_e32 v205, 15, v204
	v_lshrrev_b32_e32 v206, 4, v204
	v_lshlrev_b32_e32 v207, 1, v206
	v_xor_b32_e32 v207, v207, v205
	v_lshl_add_u32 v217, v206, 4, v207
	v_lshlrev_b32_e32 v195, 4, v217
	v_xor_b32_e32 v196, 16, v195
	v_xor_b32_e32 v208, 16, v204
	v_lshlrev_b32_e32 v208, 2, v208
	v_xor_b32_e32 v209, 32, v204
	v_lshlrev_b32_e32 v209, 2, v209
	v_mov_b32_e32 v201, 0xf149f2ca
	v_lshlrev_b32_e32 v216, 4, v206
	v_xor_b32_e32 v218, 1, v207
	v_lshlrev_b32_e32 v219, 4, v206
	s_and_b32 s1, s6, 3
	s_lshl_b32 s40, s1, 12
	s_cmp_lt_u32 s6, 4
	s_cbranch_scc0 .Lattn_roleV
	v_lshrrev_b32_e32 v220, 2, v207
	v_and_b32_e32 v221, 3, v207
	v_lshl_add_u32 v220, v220, 3, v221
	v_lshl_add_u32 v197, v220, 11, v219
	v_lshrrev_b32_e32 v220, 2, v218
	v_and_b32_e32 v221, 3, v218
	v_lshl_add_u32 v220, v220, 3, v221
	v_lshl_add_u32 v198, v220, 11, v219
	v_add_u32_e32 v198, 64, v198
	s_mov_b32 s86, s10
	s_mov_b32 s87, s11
	s_movk_i32 s20, 0x80
	s_mov_b32 s41, 0x20000
	s_branch .Lattn_roleDone
.Lattn_roleV:
	v_lshl_add_u32 v197, v207, 15, v219
	v_lshl_add_u32 v198, v218, 15, v219
	v_add_u32_e32 v198, 64, v198
	s_mov_b32 s86, s12
	s_mov_b32 s87, s13
	s_mov_b32 s20, 0x80000
	s_movk_i32 s41, 0x80
	s_or_b32 s40, s40, 0x4000
.Lattn_roleDone:
	s_mov_b32 s21, s2
.Lattn_ploop:
	s_mov_b32 s0, s21
	s_cmp_eq_u32 s7, 0
	s_cbranch_scc1 .Lattn_noperm
	s_lshl_b32 s0, s21, 3
	s_and_b32 s0, s0, 56
	s_bfe_u32 s1, s21, 0x20006
	s_or_b32 s0, s0, s1
	s_lshr_b32 s1, s21, 6
	s_and_b32 s1, s1, 0x1ffffffc
	s_add_i32 s0, s0, s1
	s_lshl_b32 s0, s0, 3
	s_bfe_u32 s1, s21, 0x30003
	s_or_b32 s0, s0, s1
.Lattn_noperm:
	s_and_b32 s36, s0, 7
	s_lshr_b32 s1, s0, 3
	s_lshr_b32 s23, s1, 3
	s_and_b32 s33, s1, 7
	s_sub_i32 s36, 15, s36
	s_mov_b32 s22, 0
.Lattn_unit:
	s_lshl_b32 s37, s36, 7
	s_lshl_b32 s0, s6, 4
	s_add_i32 s37, s37, s0
	s_lshl_b32 s0, s23, 11
	s_add_i32 s0, s0, s37
	v_add_u32_e32 v207, s0, v205
	s_lshl_b32 s1, s33, 8
	v_lshl_add_u32 v217, v207, 11, s1
	v_lshl_add_u32 v214, v206, 4, v217
	v_lshl_add_u32 v215, v206, 3, v217
	global_load_dwordx4 v[64:67], v214, s[8:9]
	global_load_dwordx4 v[68:71], v214, s[8:9] offset:64
	global_load_dwordx4 v[72:75], v214, s[8:9] offset:128
	global_load_dwordx4 v[76:79], v214, s[8:9] offset:192
	v_lshlrev_b32_e32 v218, 3, v206
	v_add_u32_e32 v200, s37, v205
	v_sub_u32_e32 v200, v200, v218
	s_cmp_lt_u32 s6, 4
	s_cbranch_scc0 .Lattn_ubV
	s_and_b32 s0, s6, 3
	s_lshr_b32 s1, s0, 1
	s_lshl_b32 s1, s1, 5
	s_and_b32 s0, s0, 1
	s_lshl_b32 s0, s0, 2
	s_add_i32 s1, s1, s0
	s_lshl_b32 s0, s23, 11
	s_add_i32 s1, s1, s0
	s_lshl_b32 s1, s1, 11
	s_lshl_b32 s0, s33, 8
	s_add_i32 s79, s1, s0
	s_branch .Lattn_ubDone
.Lattn_ubV:
	s_and_b32 s0, s6, 3
	s_lshl_b32 s0, s0, 5
	s_lshl_b32 s1, s33, 7
	s_add_i32 s0, s0, s1
	s_lshl_b32 s0, s0, 15
	s_lshl_b32 s1, s23, 12
	s_add_i32 s79, s0, s1
.Lattn_ubDone:
	v_mov_b32_e32 v0, 0
	v_mov_b32_e32 v1, 0
	v_mov_b32_e32 v2, 0
	v_mov_b32_e32 v3, 0
	v_mov_b32_e32 v4, 0
	v_mov_b32_e32 v5, 0
	v_mov_b32_e32 v6, 0
	v_mov_b32_e32 v7, 0
	v_mov_b32_e32 v8, 0
	v_mov_b32_e32 v9, 0
	v_mov_b32_e32 v10, 0
	v_mov_b32_e32 v11, 0
	v_mov_b32_e32 v12, 0
	v_mov_b32_e32 v13, 0
	v_mov_b32_e32 v14, 0
	v_mov_b32_e32 v15, 0
	v_mov_b32_e32 v16, 0
	v_mov_b32_e32 v17, 0
	v_mov_b32_e32 v18, 0
	v_mov_b32_e32 v19, 0
	v_mov_b32_e32 v20, 0
	v_mov_b32_e32 v21, 0
	v_mov_b32_e32 v22, 0
	v_mov_b32_e32 v23, 0
	v_mov_b32_e32 v24, 0
	v_mov_b32_e32 v25, 0
	v_mov_b32_e32 v26, 0
	v_mov_b32_e32 v27, 0
	v_mov_b32_e32 v28, 0
	v_mov_b32_e32 v29, 0
	v_mov_b32_e32 v30, 0
	v_mov_b32_e32 v31, 0
	v_mov_b32_e32 v32, 0
	v_mov_b32_e32 v33, 0
	v_mov_b32_e32 v34, 0
	v_mov_b32_e32 v35, 0
	v_mov_b32_e32 v36, 0
	v_mov_b32_e32 v37, 0
	v_mov_b32_e32 v38, 0
	v_mov_b32_e32 v39, 0
	v_mov_b32_e32 v40, 0
	v_mov_b32_e32 v41, 0
	v_mov_b32_e32 v42, 0
	v_mov_b32_e32 v43, 0
	v_mov_b32_e32 v44, 0
	v_mov_b32_e32 v45, 0
	v_mov_b32_e32 v46, 0
	v_mov_b32_e32 v47, 0
	v_mov_b32_e32 v48, 0
	v_mov_b32_e32 v49, 0
	v_mov_b32_e32 v50, 0
	v_mov_b32_e32 v51, 0
	v_mov_b32_e32 v52, 0
	v_mov_b32_e32 v53, 0
	v_mov_b32_e32 v54, 0
	v_mov_b32_e32 v55, 0
	v_mov_b32_e32 v56, 0
	v_mov_b32_e32 v57, 0
	v_mov_b32_e32 v58, 0
	v_mov_b32_e32 v59, 0
	v_mov_b32_e32 v60, 0
	v_mov_b32_e32 v61, 0
	v_mov_b32_e32 v62, 0
	v_mov_b32_e32 v63, 0
	v_mov_b32_e32 v193, 0
	v_mov_b32_e32 v194, 0
	s_lshl_b32 s38, s36, 1
	s_add_i32 s38, s38, 2
	s_mov_b32 s39, 0
	s_add_i32 s0, s79, s20
	v_add_u32_e32 v210, s79, v197
	v_add_u32_e32 v211, s79, v198
	v_add_u32_e32 v212, s0, v197
	v_add_u32_e32 v213, s0, v198
	s_add_i32 m0, s40, 0x0
	s_nop 0
	global_load_lds_dwordx4 v210, s[86:87]
	s_add_i32 m0, s40, 0x400
	s_nop 0
	global_load_lds_dwordx4 v211, s[86:87]
	s_add_i32 m0, s40, 0x800
	s_nop 0
	global_load_lds_dwordx4 v212, s[86:87]
	s_add_i32 m0, s40, 0xc00
	s_nop 0
	global_load_lds_dwordx4 v213, s[86:87]
	s_add_i32 s79, s79, s41
	s_waitcnt vmcnt(0)
	s_barrier
.Lattn_tile:
	s_add_i32 s0, s39, 1
	s_cmp_lt_i32 s0, s38
	s_cbranch_scc0 .Lattn_nodma
	s_and_b32 s0, s0, 1
	s_lshl_b32 s0, s0, 15
	s_add_i32 s91, s40, s0
	s_add_i32 s0, s79, s20
	v_add_u32_e32 v210, s79, v197
	v_add_u32_e32 v211, s79, v198
	v_add_u32_e32 v212, s0, v197
	v_add_u32_e32 v213, s0, v198
	s_add_i32 m0, s91, 0x0
	s_nop 0
	global_load_lds_dwordx4 v210, s[86:87]
	s_add_i32 m0, s91, 0x400
	s_nop 0
	global_load_lds_dwordx4 v211, s[86:87]
	s_add_i32 m0, s91, 0x800
	s_nop 0
	global_load_lds_dwordx4 v212, s[86:87]
	s_add_i32 m0, s91, 0xc00
	s_nop 0
	global_load_lds_dwordx4 v213, s[86:87]
	s_add_i32 s79, s79, s41
.Lattn_nodma:
	s_lshl_b32 s96, s39, 6
	s_add_i32 s0, s37, 15
	s_cmp_gt_i32 s96, s0
	s_cbranch_scc1 .Lattn_endtile
	ds_read_b128 v[80:83], v195
	ds_read_b128 v[84:87], v196 offset:1024
	ds_read_b128 v[88:91], v195 offset:4096
	ds_read_b128 v[92:95], v196 offset:5120
	ds_read_b128 v[96:99], v195 offset:8192
	ds_read_b128 v[100:103], v196 offset:9216
	ds_read_b128 v[104:107], v195 offset:12288
	ds_read_b128 v[108:111], v196 offset:13312
	s_waitcnt lgkmcnt(7)
	v_mfma_f32_16x16x32_bf16 v[144:147], v[80:83], v[64:67], v[248:251]
	ds_read_b128 v[112:115], v195 offset:2048
	s_waitcnt lgkmcnt(7)
	v_mfma_f32_16x16x32_bf16 v[144:147], v[84:87], v[68:71], v[144:147]
	ds_read_b128 v[116:119], v196 offset:3072
	s_waitcnt lgkmcnt(7)
	v_mfma_f32_16x16x32_bf16 v[148:151], v[88:91], v[64:67], v[248:251]
	ds_read_b128 v[120:123], v195 offset:6144
	s_waitcnt lgkmcnt(7)
	v_mfma_f32_16x16x32_bf16 v[148:151], v[92:95], v[68:71], v[148:151]
	ds_read_b128 v[124:127], v196 offset:7168
	s_waitcnt lgkmcnt(7)
	v_mfma_f32_16x16x32_bf16 v[152:155], v[96:99], v[64:67], v[248:251]
	ds_read_b128 v[128:131], v195 offset:10240
	s_waitcnt lgkmcnt(7)
	v_mfma_f32_16x16x32_bf16 v[152:155], v[100:103], v[68:71], v[152:155]
	ds_read_b128 v[132:135], v196 offset:11264
	s_waitcnt lgkmcnt(7)
	v_mfma_f32_16x16x32_bf16 v[156:159], v[104:107], v[64:67], v[248:251]
	ds_read_b128 v[136:139], v195 offset:14336
	s_waitcnt lgkmcnt(7)
	v_mfma_f32_16x16x32_bf16 v[156:159], v[108:111], v[68:71], v[156:159]
	ds_read_b128 v[140:143], v196 offset:15360
	s_waitcnt lgkmcnt(0)
	v_mfma_f32_16x16x32_bf16 v[160:163], v[112:115], v[72:75], v[248:251]
	v_mfma_f32_16x16x32_bf16 v[160:163], v[116:119], v[76:79], v[160:163]
	s_add_i32 s0, s96, 63
	s_cmp_gt_i32 s0, s37
	s_cselect_b32 s97, 1, 0
	s_cbranch_scc0 .Lattn_nomask0
	v_subrev_u32_e32 v207, s96, v200
	v_cmp_gt_i32_e64 s[42:43], 0, v207
	v_cmp_gt_i32_e64 s[44:45], 1, v207
	v_cmp_gt_i32_e64 s[46:47], 2, v207
	v_cmp_gt_i32_e64 s[48:49], 3, v207
	v_cmp_gt_i32_e64 s[50:51], 4, v207
	v_cmp_gt_i32_e64 s[52:53], 5, v207
	v_cmp_gt_i32_e64 s[54:55], 6, v207
	v_cmp_gt_i32_e64 s[56:57], 7, v207
	v_cmp_gt_i32_e64 s[58:59], 32, v207
	v_cmp_gt_i32_e64 s[60:61], 33, v207
	v_cmp_gt_i32_e64 s[62:63], 34, v207
	v_cmp_gt_i32_e64 s[64:65], 35, v207
	v_cmp_gt_i32_e64 s[66:67], 36, v207
	v_cmp_gt_i32_e64 s[68:69], 37, v207
	v_cmp_gt_i32_e64 s[70:71], 38, v207
	v_cmp_gt_i32_e64 s[72:73], 39, v207
	v_cndmask_b32_e64 v144, v144, v201, s[42:43]
	v_cndmask_b32_e64 v145, v145, v201, s[44:45]
	v_cndmask_b32_e64 v146, v146, v201, s[46:47]
	v_cndmask_b32_e64 v147, v147, v201, s[48:49]
	v_cndmask_b32_e64 v148, v148, v201, s[50:51]
	v_cndmask_b32_e64 v149, v149, v201, s[52:53]
	v_cndmask_b32_e64 v150, v150, v201, s[54:55]
	v_cndmask_b32_e64 v151, v151, v201, s[56:57]
	v_cndmask_b32_e64 v152, v152, v201, s[58:59]
	v_cndmask_b32_e64 v153, v153, v201, s[60:61]
	v_cndmask_b32_e64 v154, v154, v201, s[62:63]
	v_cndmask_b32_e64 v155, v155, v201, s[64:65]
	v_cndmask_b32_e64 v156, v156, v201, s[66:67]
	v_cndmask_b32_e64 v157, v157, v201, s[68:69]
	v_cndmask_b32_e64 v158, v158, v201, s[70:71]
	v_cndmask_b32_e64 v159, v159, v201, s[72:73]
.Lattn_nomask0:
	v_exp_f32_e32 v144, v144
	v_exp_f32_e32 v145, v145
	v_add_f32_e32 v193, v193, v144
	v_exp_f32_e32 v146, v146
	v_mov_b32_e32 v199, v145
	v_exp_f32_e32 v147, v147
	v_mfma_f32_16x16x32_bf16 v[164:167], v[120:123], v[72:75], v[248:251]
	v_add_f32_e32 v193, v193, v146
	v_cvt_pk_bf16_f32 v176, v144, v145
	v_exp_f32_e32 v148, v148
	v_add_f32_e32 v199, v199, v147
	v_exp_f32_e32 v149, v149
	v_add_f32_e32 v193, v193, v148
	v_mfma_f32_16x16x32_bf16 v[164:167], v[124:127], v[76:79], v[164:167]
	v_cvt_pk_bf16_f32 v177, v146, v147
	v_exp_f32_e32 v150, v150
	v_add_f32_e32 v199, v199, v149
	v_exp_f32_e32 v151, v151
	v_add_f32_e32 v193, v193, v150
	v_cvt_pk_bf16_f32 v178, v148, v149
	v_mfma_f32_16x16x32_bf16 v[168:171], v[128:131], v[72:75], v[248:251]
	v_exp_f32_e32 v152, v152
	v_add_f32_e32 v199, v199, v151
	v_exp_f32_e32 v153, v153
	v_add_f32_e32 v193, v193, v152
	v_cvt_pk_bf16_f32 v179, v150, v151
	v_mfma_f32_16x16x32_bf16 v[168:171], v[132:135], v[76:79], v[168:171]
	v_exp_f32_e32 v154, v154
	v_add_f32_e32 v199, v199, v153
	v_exp_f32_e32 v155, v155
	v_add_f32_e32 v193, v193, v154
	v_cvt_pk_bf16_f32 v180, v152, v153
	v_exp_f32_e32 v156, v156
	v_mfma_f32_16x16x32_bf16 v[172:175], v[136:139], v[72:75], v[248:251]
	v_add_f32_e32 v199, v199, v155
	v_exp_f32_e32 v157, v157
	v_add_f32_e32 v193, v193, v156
	v_cvt_pk_bf16_f32 v181, v154, v155
	v_exp_f32_e32 v158, v158
	v_add_f32_e32 v199, v199, v157
	v_mfma_f32_16x16x32_bf16 v[172:175], v[140:143], v[76:79], v[172:175]
	v_exp_f32_e32 v159, v159
	v_add_f32_e32 v193, v193, v158
	v_cvt_pk_bf16_f32 v182, v156, v157
	v_add_f32_e32 v199, v199, v159
	v_add_f32_e32 v193, v193, v199
	v_cvt_pk_bf16_f32 v183, v158, v159
	ds_read_b128 v[80:83], v195 offset:16384
	ds_read_b128 v[84:87], v196 offset:17408
	ds_read_b128 v[88:91], v195 offset:18432
	ds_read_b128 v[92:95], v196 offset:19456
	ds_read_b128 v[96:99], v195 offset:20480
	ds_read_b128 v[100:103], v196 offset:21504
	ds_read_b128 v[104:107], v195 offset:22528
	ds_read_b128 v[108:111], v196 offset:23552
	s_cmp_lg_u32 s97, 0
	s_cbranch_scc0 .Lattn_nomask1
	v_cndmask_b32_e64 v160, v160, v201, s[42:43]
	v_cndmask_b32_e64 v161, v161, v201, s[44:45]
	v_cndmask_b32_e64 v162, v162, v201, s[46:47]
	v_cndmask_b32_e64 v163, v163, v201, s[48:49]
	v_cndmask_b32_e64 v164, v164, v201, s[50:51]
	v_cndmask_b32_e64 v165, v165, v201, s[52:53]
	v_cndmask_b32_e64 v166, v166, v201, s[54:55]
	v_cndmask_b32_e64 v167, v167, v201, s[56:57]
	v_cndmask_b32_e64 v168, v168, v201, s[58:59]
	v_cndmask_b32_e64 v169, v169, v201, s[60:61]
	v_cndmask_b32_e64 v170, v170, v201, s[62:63]
	v_cndmask_b32_e64 v171, v171, v201, s[64:65]
	v_cndmask_b32_e64 v172, v172, v201, s[66:67]
	v_cndmask_b32_e64 v173, v173, v201, s[68:69]
	v_cndmask_b32_e64 v174, v174, v201, s[70:71]
	v_cndmask_b32_e64 v175, v175, v201, s[72:73]
.Lattn_nomask1:
	v_exp_f32_e32 v160, v160
	v_exp_f32_e32 v161, v161
	v_add_f32_e32 v194, v194, v160
	v_exp_f32_e32 v162, v162
	ds_read_b128 v[112:115], v195 offset:24576
	s_waitcnt lgkmcnt(8)
	v_mfma_f32_16x16x32_bf16 v[0:3], v[80:83], v[176:179], v[0:3]
	v_mov_b32_e32 v199, v161
	v_exp_f32_e32 v163, v163
	v_add_f32_e32 v194, v194, v162
	ds_read_b128 v[116:119], v196 offset:25600
	s_waitcnt lgkmcnt(8)
	v_mfma_f32_16x16x32_bf16 v[0:3], v[84:87], v[180:183], v[0:3]
	v_cvt_pk_bf16_f32 v184, v160, v161
	v_exp_f32_e32 v164, v164
	ds_read_b128 v[120:123], v195 offset:26624
	s_waitcnt lgkmcnt(8)
	v_mfma_f32_16x16x32_bf16 v[4:7], v[88:91], v[176:179], v[4:7]
	v_add_f32_e32 v199, v199, v163
	v_exp_f32_e32 v165, v165
	ds_read_b128 v[124:127], v196 offset:27648
	s_waitcnt lgkmcnt(8)
	v_mfma_f32_16x16x32_bf16 v[4:7], v[92:95], v[180:183], v[4:7]
	v_add_f32_e32 v194, v194, v164
	v_cvt_pk_bf16_f32 v185, v162, v163
	ds_read_b128 v[128:131], v195 offset:28672
	s_waitcnt lgkmcnt(8)
	v_mfma_f32_16x16x32_bf16 v[8:11], v[96:99], v[176:179], v[8:11]
	v_exp_f32_e32 v166, v166
	v_add_f32_e32 v199, v199, v165
	v_exp_f32_e32 v167, v167
	ds_read_b128 v[132:135], v196 offset:29696
	s_waitcnt lgkmcnt(8)
	v_mfma_f32_16x16x32_bf16 v[8:11], v[100:103], v[180:183], v[8:11]
	v_add_f32_e32 v194, v194, v166
	v_cvt_pk_bf16_f32 v186, v164, v165
	ds_read_b128 v[136:139], v195 offset:30720
	s_waitcnt lgkmcnt(8)
	v_mfma_f32_16x16x32_bf16 v[12:15], v[104:107], v[176:179], v[12:15]
	v_exp_f32_e32 v168, v168
	v_add_f32_e32 v199, v199, v167
	ds_read_b128 v[140:143], v196 offset:31744
	s_waitcnt lgkmcnt(8)
	v_mfma_f32_16x16x32_bf16 v[12:15], v[108:111], v[180:183], v[12:15]
	v_exp_f32_e32 v169, v169
	v_add_f32_e32 v194, v194, v168
	v_cvt_pk_bf16_f32 v187, v166, v167
	s_waitcnt lgkmcnt(7)
	v_mfma_f32_16x16x32_bf16 v[16:19], v[112:115], v[176:179], v[16:19]
	v_exp_f32_e32 v170, v170
	v_add_f32_e32 v199, v199, v169
	s_waitcnt lgkmcnt(6)
	v_mfma_f32_16x16x32_bf16 v[16:19], v[116:119], v[180:183], v[16:19]
	v_exp_f32_e32 v171, v171
	v_add_f32_e32 v194, v194, v170
	s_waitcnt lgkmcnt(5)
	v_mfma_f32_16x16x32_bf16 v[20:23], v[120:123], v[176:179], v[20:23]
	v_cvt_pk_bf16_f32 v188, v168, v169
	v_exp_f32_e32 v172, v172
	v_add_f32_e32 v199, v199, v171
	s_waitcnt lgkmcnt(4)
	v_mfma_f32_16x16x32_bf16 v[20:23], v[124:127], v[180:183], v[20:23]
	v_exp_f32_e32 v173, v173
	v_add_f32_e32 v194, v194, v172
	s_waitcnt lgkmcnt(3)
	v_mfma_f32_16x16x32_bf16 v[24:27], v[128:131], v[176:179], v[24:27]
	v_cvt_pk_bf16_f32 v189, v170, v171
	v_exp_f32_e32 v174, v174
	s_waitcnt lgkmcnt(2)
	v_mfma_f32_16x16x32_bf16 v[24:27], v[132:135], v[180:183], v[24:27]
	v_add_f32_e32 v199, v199, v173
	v_exp_f32_e32 v175, v175
	s_waitcnt lgkmcnt(1)
	v_mfma_f32_16x16x32_bf16 v[28:31], v[136:139], v[176:179], v[28:31]
	v_add_f32_e32 v194, v194, v174
	v_cvt_pk_bf16_f32 v190, v172, v173
	v_add_f32_e32 v199, v199, v175
	s_waitcnt lgkmcnt(0)
	v_mfma_f32_16x16x32_bf16 v[28:31], v[140:143], v[180:183], v[28:31]
	v_add_f32_e32 v194, v194, v199
	v_cvt_pk_bf16_f32 v191, v174, v175
	s_nop 1
	v_mfma_f32_16x16x32_bf16 v[32:35], v[80:83], v[184:187], v[32:35]
	v_mfma_f32_16x16x32_bf16 v[32:35], v[84:87], v[188:191], v[32:35]
	v_mfma_f32_16x16x32_bf16 v[36:39], v[88:91], v[184:187], v[36:39]
	v_mfma_f32_16x16x32_bf16 v[36:39], v[92:95], v[188:191], v[36:39]
	v_mfma_f32_16x16x32_bf16 v[40:43], v[96:99], v[184:187], v[40:43]
	v_mfma_f32_16x16x32_bf16 v[40:43], v[100:103], v[188:191], v[40:43]
	v_mfma_f32_16x16x32_bf16 v[44:47], v[104:107], v[184:187], v[44:47]
	v_mfma_f32_16x16x32_bf16 v[44:47], v[108:111], v[188:191], v[44:47]
	v_mfma_f32_16x16x32_bf16 v[48:51], v[112:115], v[184:187], v[48:51]
	v_mfma_f32_16x16x32_bf16 v[48:51], v[116:119], v[188:191], v[48:51]
	v_mfma_f32_16x16x32_bf16 v[52:55], v[120:123], v[184:187], v[52:55]
	v_mfma_f32_16x16x32_bf16 v[52:55], v[124:127], v[188:191], v[52:55]
	v_mfma_f32_16x16x32_bf16 v[56:59], v[128:131], v[184:187], v[56:59]
	v_mfma_f32_16x16x32_bf16 v[56:59], v[132:135], v[188:191], v[56:59]
	v_mfma_f32_16x16x32_bf16 v[60:63], v[136:139], v[184:187], v[60:63]
	v_mfma_f32_16x16x32_bf16 v[60:63], v[140:143], v[188:191], v[60:63]
.Lattn_endtile:
	s_waitcnt vmcnt(0)
	s_barrier
	v_xor_b32_e32 v195, 0x8000, v195
	v_xor_b32_e32 v196, 0x8000, v196
	s_add_i32 s39, s39, 1
	s_cmp_lt_i32 s39, s38
	s_cbranch_scc1 .Lattn_tile
	global_load_dwordx2 v[80:81], v215, s[18:19]
	global_load_dwordx2 v[82:83], v215, s[18:19] offset:32
	global_load_dwordx2 v[84:85], v215, s[18:19] offset:64
	global_load_dwordx2 v[86:87], v215, s[18:19] offset:96
	global_load_dwordx2 v[88:89], v215, s[18:19] offset:128
	global_load_dwordx2 v[90:91], v215, s[18:19] offset:160
	global_load_dwordx2 v[92:93], v215, s[18:19] offset:192
	global_load_dwordx2 v[94:95], v215, s[18:19] offset:224
	global_load_dwordx2 v[96:97], v215, s[28:29]
	global_load_dwordx2 v[112:113], v215, s[14:15]
	global_load_dwordx2 v[128:129], v215, s[16:17]
	global_load_dwordx2 v[98:99], v215, s[28:29] offset:32
	global_load_dwordx2 v[114:115], v215, s[14:15] offset:32
	global_load_dwordx2 v[130:131], v215, s[16:17] offset:32
	global_load_dwordx2 v[100:101], v215, s[28:29] offset:64
	global_load_dwordx2 v[116:117], v215, s[14:15] offset:64
	global_load_dwordx2 v[132:133], v215, s[16:17] offset:64
	global_load_dwordx2 v[102:103], v215, s[28:29] offset:96
	global_load_dwordx2 v[118:119], v215, s[14:15] offset:96
	global_load_dwordx2 v[134:135], v215, s[16:17] offset:96
	global_load_dwordx2 v[104:105], v215, s[28:29] offset:128
	global_load_dwordx2 v[120:121], v215, s[14:15] offset:128
	global_load_dwordx2 v[136:137], v215, s[16:17] offset:128
	global_load_dwordx2 v[106:107], v215, s[28:29] offset:160
	global_load_dwordx2 v[122:123], v215, s[14:15] offset:160
	global_load_dwordx2 v[138:139], v215, s[16:17] offset:160
	global_load_dwordx2 v[108:109], v215, s[28:29] offset:192
	global_load_dwordx2 v[124:125], v215, s[14:15] offset:192
	global_load_dwordx2 v[140:141], v215, s[16:17] offset:192
	global_load_dwordx2 v[110:111], v215, s[28:29] offset:224
	global_load_dwordx2 v[126:127], v215, s[14:15] offset:224
	global_load_dwordx2 v[142:143], v215, s[16:17] offset:224
	global_load_dwordx4 v[144:147], v216, s[4:5]
	global_load_dwordx4 v[148:151], v216, s[4:5] offset:64
	global_load_dwordx4 v[152:155], v216, s[4:5] offset:128
	global_load_dwordx4 v[156:159], v216, s[4:5] offset:192
	global_load_dwordx4 v[160:163], v216, s[4:5] offset:256
	global_load_dwordx4 v[164:167], v216, s[4:5] offset:320
	global_load_dwordx4 v[168:171], v216, s[4:5] offset:384
	global_load_dwordx4 v[172:175], v216, s[4:5] offset:448
	ds_bpermute_b32 v207, v208, v193
	ds_bpermute_b32 v217, v208, v194
	s_waitcnt lgkmcnt(0)
	v_add_f32_e32 v193, v193, v207
	v_add_f32_e32 v194, v194, v217
	ds_bpermute_b32 v207, v209, v193
	ds_bpermute_b32 v217, v209, v194
	s_waitcnt lgkmcnt(0)
	v_add_f32_e32 v193, v193, v207
	v_add_f32_e32 v194, v194, v217
	v_rcp_f32_e32 v222, v193
	v_rcp_f32_e32 v223, v194
	v_mov_b32_e32 v224, 0
	v_mul_f32_e32 v223, v223, v203
	v_mul_f32_e32 v32, v32, v223
	v_fma_f32 v0, v0, v222, -v32
	v_fmac_f32_e32 v224, v0, v0
	v_mul_f32_e32 v33, v33, v223
	v_fma_f32 v1, v1, v222, -v33
	v_fmac_f32_e32 v224, v1, v1
	v_mul_f32_e32 v34, v34, v223
	v_fma_f32 v2, v2, v222, -v34
	v_fmac_f32_e32 v224, v2, v2
	v_mul_f32_e32 v35, v35, v223
	v_fma_f32 v3, v3, v222, -v35
	v_fmac_f32_e32 v224, v3, v3
	v_mul_f32_e32 v36, v36, v223
	v_fma_f32 v4, v4, v222, -v36
	v_fmac_f32_e32 v224, v4, v4
	v_mul_f32_e32 v37, v37, v223
	v_fma_f32 v5, v5, v222, -v37
	v_fmac_f32_e32 v224, v5, v5
	v_mul_f32_e32 v38, v38, v223
	v_fma_f32 v6, v6, v222, -v38
	v_fmac_f32_e32 v224, v6, v6
	v_mul_f32_e32 v39, v39, v223
	v_fma_f32 v7, v7, v222, -v39
	v_fmac_f32_e32 v224, v7, v7
	v_mul_f32_e32 v40, v40, v223
	v_fma_f32 v8, v8, v222, -v40
	v_fmac_f32_e32 v224, v8, v8
	v_mul_f32_e32 v41, v41, v223
	v_fma_f32 v9, v9, v222, -v41
	v_fmac_f32_e32 v224, v9, v9
	v_mul_f32_e32 v42, v42, v223
	v_fma_f32 v10, v10, v222, -v42
	v_fmac_f32_e32 v224, v10, v10
	v_mul_f32_e32 v43, v43, v223
	v_fma_f32 v11, v11, v222, -v43
	v_fmac_f32_e32 v224, v11, v11
	v_mul_f32_e32 v44, v44, v223
	v_fma_f32 v12, v12, v222, -v44
	v_fmac_f32_e32 v224, v12, v12
	v_mul_f32_e32 v45, v45, v223
	v_fma_f32 v13, v13, v222, -v45
	v_fmac_f32_e32 v224, v13, v13
	v_mul_f32_e32 v46, v46, v223
	v_fma_f32 v14, v14, v222, -v46
	v_fmac_f32_e32 v224, v14, v14
	v_mul_f32_e32 v47, v47, v223
	v_fma_f32 v15, v15, v222, -v47
	v_fmac_f32_e32 v224, v15, v15
	v_mul_f32_e32 v48, v48, v223
	v_fma_f32 v16, v16, v222, -v48
	v_fmac_f32_e32 v224, v16, v16
	v_mul_f32_e32 v49, v49, v223
	v_fma_f32 v17, v17, v222, -v49
	v_fmac_f32_e32 v224, v17, v17
	v_mul_f32_e32 v50, v50, v223
	v_fma_f32 v18, v18, v222, -v50
	v_fmac_f32_e32 v224, v18, v18
	v_mul_f32_e32 v51, v51, v223
	v_fma_f32 v19, v19, v222, -v51
	v_fmac_f32_e32 v224, v19, v19
	v_mul_f32_e32 v52, v52, v223
	v_fma_f32 v20, v20, v222, -v52
	v_fmac_f32_e32 v224, v20, v20
	v_mul_f32_e32 v53, v53, v223
	v_fma_f32 v21, v21, v222, -v53
	v_fmac_f32_e32 v224, v21, v21
	v_mul_f32_e32 v54, v54, v223
	v_fma_f32 v22, v22, v222, -v54
	v_fmac_f32_e32 v224, v22, v22
	v_mul_f32_e32 v55, v55, v223
	v_fma_f32 v23, v23, v222, -v55
	v_fmac_f32_e32 v224, v23, v23
	v_mul_f32_e32 v56, v56, v223
	v_fma_f32 v24, v24, v222, -v56
	v_fmac_f32_e32 v224, v24, v24
	v_mul_f32_e32 v57, v57, v223
	v_fma_f32 v25, v25, v222, -v57
	v_fmac_f32_e32 v224, v25, v25
	v_mul_f32_e32 v58, v58, v223
	v_fma_f32 v26, v26, v222, -v58
	v_fmac_f32_e32 v224, v26, v26
	v_mul_f32_e32 v59, v59, v223
	v_fma_f32 v27, v27, v222, -v59
	v_fmac_f32_e32 v224, v27, v27
	v_mul_f32_e32 v60, v60, v223
	v_fma_f32 v28, v28, v222, -v60
	v_fmac_f32_e32 v224, v28, v28
	v_mul_f32_e32 v61, v61, v223
	v_fma_f32 v29, v29, v222, -v61
	v_fmac_f32_e32 v224, v29, v29
	v_mul_f32_e32 v62, v62, v223
	v_fma_f32 v30, v30, v222, -v62
	v_fmac_f32_e32 v224, v30, v30
	v_mul_f32_e32 v63, v63, v223
	v_fma_f32 v31, v31, v222, -v63
	v_fmac_f32_e32 v224, v31, v31
	global_load_dwordx4 v[32:35], v216, s[88:89]
	global_load_dwordx4 v[36:39], v216, s[88:89] offset:64
	global_load_dwordx4 v[40:43], v216, s[88:89] offset:128
	global_load_dwordx4 v[44:47], v216, s[88:89] offset:192
	global_load_dwordx4 v[48:51], v216, s[88:89] offset:256
	global_load_dwordx4 v[52:55], v216, s[88:89] offset:320
	global_load_dwordx4 v[56:59], v216, s[88:89] offset:384
	global_load_dwordx4 v[60:63], v216, s[88:89] offset:448
	s_waitcnt vmcnt(40)
	v_mov_b32_e32 v225, 0
	v_lshlrev_b32_e32 v207, 16, v80
	v_and_b32_e32 v217, 0xffff0000, v80
	v_fmac_f32_e32 v225, v207, v207
	v_fmac_f32_e32 v225, v217, v217
	v_lshlrev_b32_e32 v207, 16, v81
	v_and_b32_e32 v217, 0xffff0000, v81
	v_fmac_f32_e32 v225, v207, v207
	v_fmac_f32_e32 v225, v217, v217
	v_lshlrev_b32_e32 v207, 16, v82
	v_and_b32_e32 v217, 0xffff0000, v82
	v_fmac_f32_e32 v225, v207, v207
	v_fmac_f32_e32 v225, v217, v217
	v_lshlrev_b32_e32 v207, 16, v83
	v_and_b32_e32 v217, 0xffff0000, v83
	v_fmac_f32_e32 v225, v207, v207
	v_fmac_f32_e32 v225, v217, v217
	v_lshlrev_b32_e32 v207, 16, v84
	v_and_b32_e32 v217, 0xffff0000, v84
	v_fmac_f32_e32 v225, v207, v207
	v_fmac_f32_e32 v225, v217, v217
	v_lshlrev_b32_e32 v207, 16, v85
	v_and_b32_e32 v217, 0xffff0000, v85
	v_fmac_f32_e32 v225, v207, v207
	v_fmac_f32_e32 v225, v217, v217
	v_lshlrev_b32_e32 v207, 16, v86
	v_and_b32_e32 v217, 0xffff0000, v86
	v_fmac_f32_e32 v225, v207, v207
	v_fmac_f32_e32 v225, v217, v217
	v_lshlrev_b32_e32 v207, 16, v87
	v_and_b32_e32 v217, 0xffff0000, v87
	v_fmac_f32_e32 v225, v207, v207
	v_fmac_f32_e32 v225, v217, v217
	v_lshlrev_b32_e32 v207, 16, v88
	v_and_b32_e32 v217, 0xffff0000, v88
	v_fmac_f32_e32 v225, v207, v207
	v_fmac_f32_e32 v225, v217, v217
	v_lshlrev_b32_e32 v207, 16, v89
	v_and_b32_e32 v217, 0xffff0000, v89
	v_fmac_f32_e32 v225, v207, v207
	v_fmac_f32_e32 v225, v217, v217
	v_lshlrev_b32_e32 v207, 16, v90
	v_and_b32_e32 v217, 0xffff0000, v90
	v_fmac_f32_e32 v225, v207, v207
	v_fmac_f32_e32 v225, v217, v217
	v_lshlrev_b32_e32 v207, 16, v91
	v_and_b32_e32 v217, 0xffff0000, v91
	v_fmac_f32_e32 v225, v207, v207
	v_fmac_f32_e32 v225, v217, v217
	v_lshlrev_b32_e32 v207, 16, v92
	v_and_b32_e32 v217, 0xffff0000, v92
	v_fmac_f32_e32 v225, v207, v207
	v_fmac_f32_e32 v225, v217, v217
	v_lshlrev_b32_e32 v207, 16, v93
	v_and_b32_e32 v217, 0xffff0000, v93
	v_fmac_f32_e32 v225, v207, v207
	v_fmac_f32_e32 v225, v217, v217
	v_lshlrev_b32_e32 v207, 16, v94
	v_and_b32_e32 v217, 0xffff0000, v94
	v_fmac_f32_e32 v225, v207, v207
	v_fmac_f32_e32 v225, v217, v217
	v_lshlrev_b32_e32 v207, 16, v95
	v_and_b32_e32 v217, 0xffff0000, v95
	v_fmac_f32_e32 v225, v207, v207
	v_fmac_f32_e32 v225, v217, v217
	ds_bpermute_b32 v207, v208, v224
	ds_bpermute_b32 v217, v208, v225
	s_waitcnt lgkmcnt(0)
	v_add_f32_e32 v224, v224, v207
	v_add_f32_e32 v225, v225, v217
	ds_bpermute_b32 v207, v209, v224
	ds_bpermute_b32 v217, v209, v225
	s_waitcnt lgkmcnt(0)
	v_add_f32_e32 v224, v224, v207
	v_add_f32_e32 v225, v225, v217
	v_mov_b32_e32 v218, 0x358637bd
	v_fmac_f32_e32 v218, 0x3c000000, v224
	v_mov_b32_e32 v219, 0x358637bd
	v_fmac_f32_e32 v219, 0x3c000000, v225
	v_rsq_f32_e32 v226, v218
	v_rsq_f32_e32 v227, v219
	s_nop 0
	v_mul_f32_e32 v226, 0x3f4ccccd, v226
	s_waitcnt vmcnt(0)
	v_lshlrev_b32_e32 v176, 16, v96
	v_lshlrev_b32_e32 v177, 16, v112
	v_lshlrev_b32_e32 v178, 16, v128
	v_lshlrev_b32_e32 v179, 16, v80
	v_mul_f32_e32 v184, 0xbfb8aa3b, v176
	v_mul_f32_e32 v185, 0xbfb8aa3b, v177
	v_mul_f32_e32 v186, 0xbfb8aa3b, v178
	v_exp_f32_e32 v184, v184
	v_exp_f32_e32 v185, v185
	v_exp_f32_e32 v186, v186
	v_mul_f32_e32 v179, v179, v227
	v_add_f32_e32 v184, 1.0, v184
	v_add_f32_e32 v185, 1.0, v185
	v_add_f32_e32 v186, 1.0, v186
	v_rcp_f32_e32 v184, v184
	v_rcp_f32_e32 v185, v185
	v_rcp_f32_e32 v186, v186
	v_mul_f32_e32 v179, v179, v32
	v_mul_f32_e32 v176, v176, v184
	v_mul_f32_e32 v178, v0, v226
	v_mul_f32_e32 v179, v179, v176
	v_mul_f32_e32 v178, v178, v144
	v_mul_f32_e32 v179, v179, v185
	v_fmac_f32_e32 v179, v186, v178
	v_and_b32_e32 v180, 0xffff0000, v96
	v_and_b32_e32 v181, 0xffff0000, v112
	v_and_b32_e32 v182, 0xffff0000, v128
	v_and_b32_e32 v183, 0xffff0000, v80
	v_mul_f32_e32 v187, 0xbfb8aa3b, v180
	v_mul_f32_e32 v188, 0xbfb8aa3b, v181
	v_mul_f32_e32 v189, 0xbfb8aa3b, v182
	v_exp_f32_e32 v187, v187
	v_exp_f32_e32 v188, v188
	v_exp_f32_e32 v189, v189
	v_mul_f32_e32 v183, v183, v227
	v_add_f32_e32 v187, 1.0, v187
	v_add_f32_e32 v188, 1.0, v188
	v_add_f32_e32 v189, 1.0, v189
	v_rcp_f32_e32 v187, v187
	v_rcp_f32_e32 v188, v188
	v_rcp_f32_e32 v189, v189
	v_mul_f32_e32 v183, v183, v33
	v_mul_f32_e32 v180, v180, v187
	v_mul_f32_e32 v182, v1, v226
	v_mul_f32_e32 v183, v183, v180
	v_mul_f32_e32 v182, v182, v145
	v_mul_f32_e32 v183, v183, v188
	v_fmac_f32_e32 v183, v189, v182
	v_cvt_pk_bf16_f32 v190, v179, v183
	v_lshlrev_b32_e32 v176, 16, v97
	v_lshlrev_b32_e32 v177, 16, v113
	v_lshlrev_b32_e32 v178, 16, v129
	v_lshlrev_b32_e32 v179, 16, v81
	v_mul_f32_e32 v184, 0xbfb8aa3b, v176
	v_mul_f32_e32 v185, 0xbfb8aa3b, v177
	v_mul_f32_e32 v186, 0xbfb8aa3b, v178
	v_exp_f32_e32 v184, v184
	v_exp_f32_e32 v185, v185
	v_exp_f32_e32 v186, v186
	v_mul_f32_e32 v179, v179, v227
	v_add_f32_e32 v184, 1.0, v184
	v_add_f32_e32 v185, 1.0, v185
	v_add_f32_e32 v186, 1.0, v186
	v_rcp_f32_e32 v184, v184
	v_rcp_f32_e32 v185, v185
	v_rcp_f32_e32 v186, v186
	v_mul_f32_e32 v179, v179, v34
	v_mul_f32_e32 v176, v176, v184
	v_mul_f32_e32 v178, v2, v226
	v_mul_f32_e32 v179, v179, v176
	v_mul_f32_e32 v178, v178, v146
	v_mul_f32_e32 v179, v179, v185
	v_fmac_f32_e32 v179, v186, v178
	v_and_b32_e32 v180, 0xffff0000, v97
	v_and_b32_e32 v181, 0xffff0000, v113
	v_and_b32_e32 v182, 0xffff0000, v129
	v_and_b32_e32 v183, 0xffff0000, v81
	v_mul_f32_e32 v187, 0xbfb8aa3b, v180
	v_mul_f32_e32 v188, 0xbfb8aa3b, v181
	v_mul_f32_e32 v189, 0xbfb8aa3b, v182
	v_exp_f32_e32 v187, v187
	v_exp_f32_e32 v188, v188
	v_exp_f32_e32 v189, v189
	v_mul_f32_e32 v183, v183, v227
	v_add_f32_e32 v187, 1.0, v187
	v_add_f32_e32 v188, 1.0, v188
	v_add_f32_e32 v189, 1.0, v189
	v_rcp_f32_e32 v187, v187
	v_rcp_f32_e32 v188, v188
	v_rcp_f32_e32 v189, v189
	v_mul_f32_e32 v183, v183, v35
	v_mul_f32_e32 v180, v180, v187
	v_mul_f32_e32 v182, v3, v226
	v_mul_f32_e32 v183, v183, v180
	v_mul_f32_e32 v182, v182, v147
	v_mul_f32_e32 v183, v183, v188
	v_fmac_f32_e32 v183, v189, v182
	v_cvt_pk_bf16_f32 v191, v179, v183
	global_store_dwordx2 v215, v[190:191], s[28:29]
	s_nop 1
	v_lshlrev_b32_e32 v176, 16, v98
	v_lshlrev_b32_e32 v177, 16, v114
	v_lshlrev_b32_e32 v178, 16, v130
	v_lshlrev_b32_e32 v179, 16, v82
	v_mul_f32_e32 v184, 0xbfb8aa3b, v176
	v_mul_f32_e32 v185, 0xbfb8aa3b, v177
	v_mul_f32_e32 v186, 0xbfb8aa3b, v178
	v_exp_f32_e32 v184, v184
	v_exp_f32_e32 v185, v185
	v_exp_f32_e32 v186, v186
	v_mul_f32_e32 v179, v179, v227
	v_add_f32_e32 v184, 1.0, v184
	v_add_f32_e32 v185, 1.0, v185
	v_add_f32_e32 v186, 1.0, v186
	v_rcp_f32_e32 v184, v184
	v_rcp_f32_e32 v185, v185
	v_rcp_f32_e32 v186, v186
	v_mul_f32_e32 v179, v179, v36
	v_mul_f32_e32 v176, v176, v184
	v_mul_f32_e32 v178, v4, v226
	v_mul_f32_e32 v179, v179, v176
	v_mul_f32_e32 v178, v178, v148
	v_mul_f32_e32 v179, v179, v185
	v_fmac_f32_e32 v179, v186, v178
	v_and_b32_e32 v180, 0xffff0000, v98
	v_and_b32_e32 v181, 0xffff0000, v114
	v_and_b32_e32 v182, 0xffff0000, v130
	v_and_b32_e32 v183, 0xffff0000, v82
	v_mul_f32_e32 v187, 0xbfb8aa3b, v180
	v_mul_f32_e32 v188, 0xbfb8aa3b, v181
	v_mul_f32_e32 v189, 0xbfb8aa3b, v182
	v_exp_f32_e32 v187, v187
	v_exp_f32_e32 v188, v188
	v_exp_f32_e32 v189, v189
	v_mul_f32_e32 v183, v183, v227
	v_add_f32_e32 v187, 1.0, v187
	v_add_f32_e32 v188, 1.0, v188
	v_add_f32_e32 v189, 1.0, v189
	v_rcp_f32_e32 v187, v187
	v_rcp_f32_e32 v188, v188
	v_rcp_f32_e32 v189, v189
	v_mul_f32_e32 v183, v183, v37
	v_mul_f32_e32 v180, v180, v187
	v_mul_f32_e32 v182, v5, v226
	v_mul_f32_e32 v183, v183, v180
	v_mul_f32_e32 v182, v182, v149
	v_mul_f32_e32 v183, v183, v188
	v_fmac_f32_e32 v183, v189, v182
	v_cvt_pk_bf16_f32 v190, v179, v183
	v_lshlrev_b32_e32 v176, 16, v99
	v_lshlrev_b32_e32 v177, 16, v115
	v_lshlrev_b32_e32 v178, 16, v131
	v_lshlrev_b32_e32 v179, 16, v83
	v_mul_f32_e32 v184, 0xbfb8aa3b, v176
	v_mul_f32_e32 v185, 0xbfb8aa3b, v177
	v_mul_f32_e32 v186, 0xbfb8aa3b, v178
	v_exp_f32_e32 v184, v184
	v_exp_f32_e32 v185, v185
	v_exp_f32_e32 v186, v186
	v_mul_f32_e32 v179, v179, v227
	v_add_f32_e32 v184, 1.0, v184
	v_add_f32_e32 v185, 1.0, v185
	v_add_f32_e32 v186, 1.0, v186
	v_rcp_f32_e32 v184, v184
	v_rcp_f32_e32 v185, v185
	v_rcp_f32_e32 v186, v186
	v_mul_f32_e32 v179, v179, v38
	v_mul_f32_e32 v176, v176, v184
	v_mul_f32_e32 v178, v6, v226
	v_mul_f32_e32 v179, v179, v176
	v_mul_f32_e32 v178, v178, v150
	v_mul_f32_e32 v179, v179, v185
	v_fmac_f32_e32 v179, v186, v178
	v_and_b32_e32 v180, 0xffff0000, v99
	v_and_b32_e32 v181, 0xffff0000, v115
	v_and_b32_e32 v182, 0xffff0000, v131
	v_and_b32_e32 v183, 0xffff0000, v83
	v_mul_f32_e32 v187, 0xbfb8aa3b, v180
	v_mul_f32_e32 v188, 0xbfb8aa3b, v181
	v_mul_f32_e32 v189, 0xbfb8aa3b, v182
	v_exp_f32_e32 v187, v187
	v_exp_f32_e32 v188, v188
	v_exp_f32_e32 v189, v189
	v_mul_f32_e32 v183, v183, v227
	v_add_f32_e32 v187, 1.0, v187
	v_add_f32_e32 v188, 1.0, v188
	v_add_f32_e32 v189, 1.0, v189
	v_rcp_f32_e32 v187, v187
	v_rcp_f32_e32 v188, v188
	v_rcp_f32_e32 v189, v189
	v_mul_f32_e32 v183, v183, v39
	v_mul_f32_e32 v180, v180, v187
	v_mul_f32_e32 v182, v7, v226
	v_mul_f32_e32 v183, v183, v180
	v_mul_f32_e32 v182, v182, v151
	v_mul_f32_e32 v183, v183, v188
	v_fmac_f32_e32 v183, v189, v182
	v_cvt_pk_bf16_f32 v191, v179, v183
	global_store_dwordx2 v215, v[190:191], s[28:29] offset:32
	s_nop 1
	v_lshlrev_b32_e32 v176, 16, v100
	v_lshlrev_b32_e32 v177, 16, v116
	v_lshlrev_b32_e32 v178, 16, v132
	v_lshlrev_b32_e32 v179, 16, v84
	v_mul_f32_e32 v184, 0xbfb8aa3b, v176
	v_mul_f32_e32 v185, 0xbfb8aa3b, v177
	v_mul_f32_e32 v186, 0xbfb8aa3b, v178
	v_exp_f32_e32 v184, v184
	v_exp_f32_e32 v185, v185
	v_exp_f32_e32 v186, v186
	v_mul_f32_e32 v179, v179, v227
	v_add_f32_e32 v184, 1.0, v184
	v_add_f32_e32 v185, 1.0, v185
	v_add_f32_e32 v186, 1.0, v186
	v_rcp_f32_e32 v184, v184
	v_rcp_f32_e32 v185, v185
	v_rcp_f32_e32 v186, v186
	v_mul_f32_e32 v179, v179, v40
	v_mul_f32_e32 v176, v176, v184
	v_mul_f32_e32 v178, v8, v226
	v_mul_f32_e32 v179, v179, v176
	v_mul_f32_e32 v178, v178, v152
	v_mul_f32_e32 v179, v179, v185
	v_fmac_f32_e32 v179, v186, v178
	v_and_b32_e32 v180, 0xffff0000, v100
	v_and_b32_e32 v181, 0xffff0000, v116
	v_and_b32_e32 v182, 0xffff0000, v132
	v_and_b32_e32 v183, 0xffff0000, v84
	v_mul_f32_e32 v187, 0xbfb8aa3b, v180
	v_mul_f32_e32 v188, 0xbfb8aa3b, v181
	v_mul_f32_e32 v189, 0xbfb8aa3b, v182
	v_exp_f32_e32 v187, v187
	v_exp_f32_e32 v188, v188
	v_exp_f32_e32 v189, v189
	v_mul_f32_e32 v183, v183, v227
	v_add_f32_e32 v187, 1.0, v187
	v_add_f32_e32 v188, 1.0, v188
	v_add_f32_e32 v189, 1.0, v189
	v_rcp_f32_e32 v187, v187
	v_rcp_f32_e32 v188, v188
	v_rcp_f32_e32 v189, v189
	v_mul_f32_e32 v183, v183, v41
	v_mul_f32_e32 v180, v180, v187
	v_mul_f32_e32 v182, v9, v226
	v_mul_f32_e32 v183, v183, v180
	v_mul_f32_e32 v182, v182, v153
	v_mul_f32_e32 v183, v183, v188
	v_fmac_f32_e32 v183, v189, v182
	v_cvt_pk_bf16_f32 v190, v179, v183
	v_lshlrev_b32_e32 v176, 16, v101
	v_lshlrev_b32_e32 v177, 16, v117
	v_lshlrev_b32_e32 v178, 16, v133
	v_lshlrev_b32_e32 v179, 16, v85
	v_mul_f32_e32 v184, 0xbfb8aa3b, v176
	v_mul_f32_e32 v185, 0xbfb8aa3b, v177
	v_mul_f32_e32 v186, 0xbfb8aa3b, v178
	v_exp_f32_e32 v184, v184
	v_exp_f32_e32 v185, v185
	v_exp_f32_e32 v186, v186
	v_mul_f32_e32 v179, v179, v227
	v_add_f32_e32 v184, 1.0, v184
	v_add_f32_e32 v185, 1.0, v185
	v_add_f32_e32 v186, 1.0, v186
	v_rcp_f32_e32 v184, v184
	v_rcp_f32_e32 v185, v185
	v_rcp_f32_e32 v186, v186
	v_mul_f32_e32 v179, v179, v42
	v_mul_f32_e32 v176, v176, v184
	v_mul_f32_e32 v178, v10, v226
	v_mul_f32_e32 v179, v179, v176
	v_mul_f32_e32 v178, v178, v154
	v_mul_f32_e32 v179, v179, v185
	v_fmac_f32_e32 v179, v186, v178
	v_and_b32_e32 v180, 0xffff0000, v101
	v_and_b32_e32 v181, 0xffff0000, v117
	v_and_b32_e32 v182, 0xffff0000, v133
	v_and_b32_e32 v183, 0xffff0000, v85
	v_mul_f32_e32 v187, 0xbfb8aa3b, v180
	v_mul_f32_e32 v188, 0xbfb8aa3b, v181
	v_mul_f32_e32 v189, 0xbfb8aa3b, v182
	v_exp_f32_e32 v187, v187
	v_exp_f32_e32 v188, v188
	v_exp_f32_e32 v189, v189
	v_mul_f32_e32 v183, v183, v227
	v_add_f32_e32 v187, 1.0, v187
	v_add_f32_e32 v188, 1.0, v188
	v_add_f32_e32 v189, 1.0, v189
	v_rcp_f32_e32 v187, v187
	v_rcp_f32_e32 v188, v188
	v_rcp_f32_e32 v189, v189
	v_mul_f32_e32 v183, v183, v43
	v_mul_f32_e32 v180, v180, v187
	v_mul_f32_e32 v182, v11, v226
	v_mul_f32_e32 v183, v183, v180
	v_mul_f32_e32 v182, v182, v155
	v_mul_f32_e32 v183, v183, v188
	v_fmac_f32_e32 v183, v189, v182
	v_cvt_pk_bf16_f32 v191, v179, v183
	global_store_dwordx2 v215, v[190:191], s[28:29] offset:64
	s_nop 1
	v_lshlrev_b32_e32 v176, 16, v102
	v_lshlrev_b32_e32 v177, 16, v118
	v_lshlrev_b32_e32 v178, 16, v134
	v_lshlrev_b32_e32 v179, 16, v86
	v_mul_f32_e32 v184, 0xbfb8aa3b, v176
	v_mul_f32_e32 v185, 0xbfb8aa3b, v177
	v_mul_f32_e32 v186, 0xbfb8aa3b, v178
	v_exp_f32_e32 v184, v184
	v_exp_f32_e32 v185, v185
	v_exp_f32_e32 v186, v186
	v_mul_f32_e32 v179, v179, v227
	v_add_f32_e32 v184, 1.0, v184
	v_add_f32_e32 v185, 1.0, v185
	v_add_f32_e32 v186, 1.0, v186
	v_rcp_f32_e32 v184, v184
	v_rcp_f32_e32 v185, v185
	v_rcp_f32_e32 v186, v186
	v_mul_f32_e32 v179, v179, v44
	v_mul_f32_e32 v176, v176, v184
	v_mul_f32_e32 v178, v12, v226
	v_mul_f32_e32 v179, v179, v176
	v_mul_f32_e32 v178, v178, v156
	v_mul_f32_e32 v179, v179, v185
	v_fmac_f32_e32 v179, v186, v178
	v_and_b32_e32 v180, 0xffff0000, v102
	v_and_b32_e32 v181, 0xffff0000, v118
	v_and_b32_e32 v182, 0xffff0000, v134
	v_and_b32_e32 v183, 0xffff0000, v86
	v_mul_f32_e32 v187, 0xbfb8aa3b, v180
	v_mul_f32_e32 v188, 0xbfb8aa3b, v181
	v_mul_f32_e32 v189, 0xbfb8aa3b, v182
	v_exp_f32_e32 v187, v187
	v_exp_f32_e32 v188, v188
	v_exp_f32_e32 v189, v189
	v_mul_f32_e32 v183, v183, v227
	v_add_f32_e32 v187, 1.0, v187
	v_add_f32_e32 v188, 1.0, v188
	v_add_f32_e32 v189, 1.0, v189
	v_rcp_f32_e32 v187, v187
	v_rcp_f32_e32 v188, v188
	v_rcp_f32_e32 v189, v189
	v_mul_f32_e32 v183, v183, v45
	v_mul_f32_e32 v180, v180, v187
	v_mul_f32_e32 v182, v13, v226
	v_mul_f32_e32 v183, v183, v180
	v_mul_f32_e32 v182, v182, v157
	v_mul_f32_e32 v183, v183, v188
	v_fmac_f32_e32 v183, v189, v182
	v_cvt_pk_bf16_f32 v190, v179, v183
	v_lshlrev_b32_e32 v176, 16, v103
	v_lshlrev_b32_e32 v177, 16, v119
	v_lshlrev_b32_e32 v178, 16, v135
	v_lshlrev_b32_e32 v179, 16, v87
	v_mul_f32_e32 v184, 0xbfb8aa3b, v176
	v_mul_f32_e32 v185, 0xbfb8aa3b, v177
	v_mul_f32_e32 v186, 0xbfb8aa3b, v178
	v_exp_f32_e32 v184, v184
	v_exp_f32_e32 v185, v185
	v_exp_f32_e32 v186, v186
	v_mul_f32_e32 v179, v179, v227
	v_add_f32_e32 v184, 1.0, v184
	v_add_f32_e32 v185, 1.0, v185
	v_add_f32_e32 v186, 1.0, v186
	v_rcp_f32_e32 v184, v184
	v_rcp_f32_e32 v185, v185
	v_rcp_f32_e32 v186, v186
	v_mul_f32_e32 v179, v179, v46
	v_mul_f32_e32 v176, v176, v184
	v_mul_f32_e32 v178, v14, v226
	v_mul_f32_e32 v179, v179, v176
	v_mul_f32_e32 v178, v178, v158
	v_mul_f32_e32 v179, v179, v185
	v_fmac_f32_e32 v179, v186, v178
	v_and_b32_e32 v180, 0xffff0000, v103
	v_and_b32_e32 v181, 0xffff0000, v119
	v_and_b32_e32 v182, 0xffff0000, v135
	v_and_b32_e32 v183, 0xffff0000, v87
	v_mul_f32_e32 v187, 0xbfb8aa3b, v180
	v_mul_f32_e32 v188, 0xbfb8aa3b, v181
	v_mul_f32_e32 v189, 0xbfb8aa3b, v182
	v_exp_f32_e32 v187, v187
	v_exp_f32_e32 v188, v188
	v_exp_f32_e32 v189, v189
	v_mul_f32_e32 v183, v183, v227
	v_add_f32_e32 v187, 1.0, v187
	v_add_f32_e32 v188, 1.0, v188
	v_add_f32_e32 v189, 1.0, v189
	v_rcp_f32_e32 v187, v187
	v_rcp_f32_e32 v188, v188
	v_rcp_f32_e32 v189, v189
	v_mul_f32_e32 v183, v183, v47
	v_mul_f32_e32 v180, v180, v187
	v_mul_f32_e32 v182, v15, v226
	v_mul_f32_e32 v183, v183, v180
	v_mul_f32_e32 v182, v182, v159
	v_mul_f32_e32 v183, v183, v188
	v_fmac_f32_e32 v183, v189, v182
	v_cvt_pk_bf16_f32 v191, v179, v183
	global_store_dwordx2 v215, v[190:191], s[28:29] offset:96
	s_nop 1
	v_lshlrev_b32_e32 v176, 16, v104
	v_lshlrev_b32_e32 v177, 16, v120
	v_lshlrev_b32_e32 v178, 16, v136
	v_lshlrev_b32_e32 v179, 16, v88
	v_mul_f32_e32 v184, 0xbfb8aa3b, v176
	v_mul_f32_e32 v185, 0xbfb8aa3b, v177
	v_mul_f32_e32 v186, 0xbfb8aa3b, v178
	v_exp_f32_e32 v184, v184
	v_exp_f32_e32 v185, v185
	v_exp_f32_e32 v186, v186
	v_mul_f32_e32 v179, v179, v227
	v_add_f32_e32 v184, 1.0, v184
	v_add_f32_e32 v185, 1.0, v185
	v_add_f32_e32 v186, 1.0, v186
	v_rcp_f32_e32 v184, v184
	v_rcp_f32_e32 v185, v185
	v_rcp_f32_e32 v186, v186
	v_mul_f32_e32 v179, v179, v48
	v_mul_f32_e32 v176, v176, v184
	v_mul_f32_e32 v178, v16, v226
	v_mul_f32_e32 v179, v179, v176
	v_mul_f32_e32 v178, v178, v160
	v_mul_f32_e32 v179, v179, v185
	v_fmac_f32_e32 v179, v186, v178
	v_and_b32_e32 v180, 0xffff0000, v104
	v_and_b32_e32 v181, 0xffff0000, v120
	v_and_b32_e32 v182, 0xffff0000, v136
	v_and_b32_e32 v183, 0xffff0000, v88
	v_mul_f32_e32 v187, 0xbfb8aa3b, v180
	v_mul_f32_e32 v188, 0xbfb8aa3b, v181
	v_mul_f32_e32 v189, 0xbfb8aa3b, v182
	v_exp_f32_e32 v187, v187
	v_exp_f32_e32 v188, v188
	v_exp_f32_e32 v189, v189
	v_mul_f32_e32 v183, v183, v227
	v_add_f32_e32 v187, 1.0, v187
	v_add_f32_e32 v188, 1.0, v188
	v_add_f32_e32 v189, 1.0, v189
	v_rcp_f32_e32 v187, v187
	v_rcp_f32_e32 v188, v188
	v_rcp_f32_e32 v189, v189
	v_mul_f32_e32 v183, v183, v49
	v_mul_f32_e32 v180, v180, v187
	v_mul_f32_e32 v182, v17, v226
	v_mul_f32_e32 v183, v183, v180
	v_mul_f32_e32 v182, v182, v161
	v_mul_f32_e32 v183, v183, v188
	v_fmac_f32_e32 v183, v189, v182
	v_cvt_pk_bf16_f32 v190, v179, v183
	v_lshlrev_b32_e32 v176, 16, v105
	v_lshlrev_b32_e32 v177, 16, v121
	v_lshlrev_b32_e32 v178, 16, v137
	v_lshlrev_b32_e32 v179, 16, v89
	v_mul_f32_e32 v184, 0xbfb8aa3b, v176
	v_mul_f32_e32 v185, 0xbfb8aa3b, v177
	v_mul_f32_e32 v186, 0xbfb8aa3b, v178
	v_exp_f32_e32 v184, v184
	v_exp_f32_e32 v185, v185
	v_exp_f32_e32 v186, v186
	v_mul_f32_e32 v179, v179, v227
	v_add_f32_e32 v184, 1.0, v184
	v_add_f32_e32 v185, 1.0, v185
	v_add_f32_e32 v186, 1.0, v186
	v_rcp_f32_e32 v184, v184
	v_rcp_f32_e32 v185, v185
	v_rcp_f32_e32 v186, v186
	v_mul_f32_e32 v179, v179, v50
	v_mul_f32_e32 v176, v176, v184
	v_mul_f32_e32 v178, v18, v226
	v_mul_f32_e32 v179, v179, v176
	v_mul_f32_e32 v178, v178, v162
	v_mul_f32_e32 v179, v179, v185
	v_fmac_f32_e32 v179, v186, v178
	v_and_b32_e32 v180, 0xffff0000, v105
	v_and_b32_e32 v181, 0xffff0000, v121
	v_and_b32_e32 v182, 0xffff0000, v137
	v_and_b32_e32 v183, 0xffff0000, v89
	v_mul_f32_e32 v187, 0xbfb8aa3b, v180
	v_mul_f32_e32 v188, 0xbfb8aa3b, v181
	v_mul_f32_e32 v189, 0xbfb8aa3b, v182
	v_exp_f32_e32 v187, v187
	v_exp_f32_e32 v188, v188
	v_exp_f32_e32 v189, v189
	v_mul_f32_e32 v183, v183, v227
	v_add_f32_e32 v187, 1.0, v187
	v_add_f32_e32 v188, 1.0, v188
	v_add_f32_e32 v189, 1.0, v189
	v_rcp_f32_e32 v187, v187
	v_rcp_f32_e32 v188, v188
	v_rcp_f32_e32 v189, v189
	v_mul_f32_e32 v183, v183, v51
	v_mul_f32_e32 v180, v180, v187
	v_mul_f32_e32 v182, v19, v226
	v_mul_f32_e32 v183, v183, v180
	v_mul_f32_e32 v182, v182, v163
	v_mul_f32_e32 v183, v183, v188
	v_fmac_f32_e32 v183, v189, v182
	v_cvt_pk_bf16_f32 v191, v179, v183
	global_store_dwordx2 v215, v[190:191], s[28:29] offset:128
	s_nop 1
	v_lshlrev_b32_e32 v176, 16, v106
	v_lshlrev_b32_e32 v177, 16, v122
	v_lshlrev_b32_e32 v178, 16, v138
	v_lshlrev_b32_e32 v179, 16, v90
	v_mul_f32_e32 v184, 0xbfb8aa3b, v176
	v_mul_f32_e32 v185, 0xbfb8aa3b, v177
	v_mul_f32_e32 v186, 0xbfb8aa3b, v178
	v_exp_f32_e32 v184, v184
	v_exp_f32_e32 v185, v185
	v_exp_f32_e32 v186, v186
	v_mul_f32_e32 v179, v179, v227
	v_add_f32_e32 v184, 1.0, v184
	v_add_f32_e32 v185, 1.0, v185
	v_add_f32_e32 v186, 1.0, v186
	v_rcp_f32_e32 v184, v184
	v_rcp_f32_e32 v185, v185
	v_rcp_f32_e32 v186, v186
	v_mul_f32_e32 v179, v179, v52
	v_mul_f32_e32 v176, v176, v184
	v_mul_f32_e32 v178, v20, v226
	v_mul_f32_e32 v179, v179, v176
	v_mul_f32_e32 v178, v178, v164
	v_mul_f32_e32 v179, v179, v185
	v_fmac_f32_e32 v179, v186, v178
	v_and_b32_e32 v180, 0xffff0000, v106
	v_and_b32_e32 v181, 0xffff0000, v122
	v_and_b32_e32 v182, 0xffff0000, v138
	v_and_b32_e32 v183, 0xffff0000, v90
	v_mul_f32_e32 v187, 0xbfb8aa3b, v180
	v_mul_f32_e32 v188, 0xbfb8aa3b, v181
	v_mul_f32_e32 v189, 0xbfb8aa3b, v182
	v_exp_f32_e32 v187, v187
	v_exp_f32_e32 v188, v188
	v_exp_f32_e32 v189, v189
	v_mul_f32_e32 v183, v183, v227
	v_add_f32_e32 v187, 1.0, v187
	v_add_f32_e32 v188, 1.0, v188
	v_add_f32_e32 v189, 1.0, v189
	v_rcp_f32_e32 v187, v187
	v_rcp_f32_e32 v188, v188
	v_rcp_f32_e32 v189, v189
	v_mul_f32_e32 v183, v183, v53
	v_mul_f32_e32 v180, v180, v187
	v_mul_f32_e32 v182, v21, v226
	v_mul_f32_e32 v183, v183, v180
	v_mul_f32_e32 v182, v182, v165
	v_mul_f32_e32 v183, v183, v188
	v_fmac_f32_e32 v183, v189, v182
	v_cvt_pk_bf16_f32 v190, v179, v183
	v_lshlrev_b32_e32 v176, 16, v107
	v_lshlrev_b32_e32 v177, 16, v123
	v_lshlrev_b32_e32 v178, 16, v139
	v_lshlrev_b32_e32 v179, 16, v91
	v_mul_f32_e32 v184, 0xbfb8aa3b, v176
	v_mul_f32_e32 v185, 0xbfb8aa3b, v177
	v_mul_f32_e32 v186, 0xbfb8aa3b, v178
	v_exp_f32_e32 v184, v184
	v_exp_f32_e32 v185, v185
	v_exp_f32_e32 v186, v186
	v_mul_f32_e32 v179, v179, v227
	v_add_f32_e32 v184, 1.0, v184
	v_add_f32_e32 v185, 1.0, v185
	v_add_f32_e32 v186, 1.0, v186
	v_rcp_f32_e32 v184, v184
	v_rcp_f32_e32 v185, v185
	v_rcp_f32_e32 v186, v186
	v_mul_f32_e32 v179, v179, v54
	v_mul_f32_e32 v176, v176, v184
	v_mul_f32_e32 v178, v22, v226
	v_mul_f32_e32 v179, v179, v176
	v_mul_f32_e32 v178, v178, v166
	v_mul_f32_e32 v179, v179, v185
	v_fmac_f32_e32 v179, v186, v178
	v_and_b32_e32 v180, 0xffff0000, v107
	v_and_b32_e32 v181, 0xffff0000, v123
	v_and_b32_e32 v182, 0xffff0000, v139
	v_and_b32_e32 v183, 0xffff0000, v91
	v_mul_f32_e32 v187, 0xbfb8aa3b, v180
	v_mul_f32_e32 v188, 0xbfb8aa3b, v181
	v_mul_f32_e32 v189, 0xbfb8aa3b, v182
	v_exp_f32_e32 v187, v187
	v_exp_f32_e32 v188, v188
	v_exp_f32_e32 v189, v189
	v_mul_f32_e32 v183, v183, v227
	v_add_f32_e32 v187, 1.0, v187
	v_add_f32_e32 v188, 1.0, v188
	v_add_f32_e32 v189, 1.0, v189
	v_rcp_f32_e32 v187, v187
	v_rcp_f32_e32 v188, v188
	v_rcp_f32_e32 v189, v189
	v_mul_f32_e32 v183, v183, v55
	v_mul_f32_e32 v180, v180, v187
	v_mul_f32_e32 v182, v23, v226
	v_mul_f32_e32 v183, v183, v180
	v_mul_f32_e32 v182, v182, v167
	v_mul_f32_e32 v183, v183, v188
	v_fmac_f32_e32 v183, v189, v182
	v_cvt_pk_bf16_f32 v191, v179, v183
	global_store_dwordx2 v215, v[190:191], s[28:29] offset:160
	s_nop 1
	v_lshlrev_b32_e32 v176, 16, v108
	v_lshlrev_b32_e32 v177, 16, v124
	v_lshlrev_b32_e32 v178, 16, v140
	v_lshlrev_b32_e32 v179, 16, v92
	v_mul_f32_e32 v184, 0xbfb8aa3b, v176
	v_mul_f32_e32 v185, 0xbfb8aa3b, v177
	v_mul_f32_e32 v186, 0xbfb8aa3b, v178
	v_exp_f32_e32 v184, v184
	v_exp_f32_e32 v185, v185
	v_exp_f32_e32 v186, v186
	v_mul_f32_e32 v179, v179, v227
	v_add_f32_e32 v184, 1.0, v184
	v_add_f32_e32 v185, 1.0, v185
	v_add_f32_e32 v186, 1.0, v186
	v_rcp_f32_e32 v184, v184
	v_rcp_f32_e32 v185, v185
	v_rcp_f32_e32 v186, v186
	v_mul_f32_e32 v179, v179, v56
	v_mul_f32_e32 v176, v176, v184
	v_mul_f32_e32 v178, v24, v226
	v_mul_f32_e32 v179, v179, v176
	v_mul_f32_e32 v178, v178, v168
	v_mul_f32_e32 v179, v179, v185
	v_fmac_f32_e32 v179, v186, v178
	v_and_b32_e32 v180, 0xffff0000, v108
	v_and_b32_e32 v181, 0xffff0000, v124
	v_and_b32_e32 v182, 0xffff0000, v140
	v_and_b32_e32 v183, 0xffff0000, v92
	v_mul_f32_e32 v187, 0xbfb8aa3b, v180
	v_mul_f32_e32 v188, 0xbfb8aa3b, v181
	v_mul_f32_e32 v189, 0xbfb8aa3b, v182
	v_exp_f32_e32 v187, v187
	v_exp_f32_e32 v188, v188
	v_exp_f32_e32 v189, v189
	v_mul_f32_e32 v183, v183, v227
	v_add_f32_e32 v187, 1.0, v187
	v_add_f32_e32 v188, 1.0, v188
	v_add_f32_e32 v189, 1.0, v189
	v_rcp_f32_e32 v187, v187
	v_rcp_f32_e32 v188, v188
	v_rcp_f32_e32 v189, v189
	v_mul_f32_e32 v183, v183, v57
	v_mul_f32_e32 v180, v180, v187
	v_mul_f32_e32 v182, v25, v226
	v_mul_f32_e32 v183, v183, v180
	v_mul_f32_e32 v182, v182, v169
	v_mul_f32_e32 v183, v183, v188
	v_fmac_f32_e32 v183, v189, v182
	v_cvt_pk_bf16_f32 v190, v179, v183
	v_lshlrev_b32_e32 v176, 16, v109
	v_lshlrev_b32_e32 v177, 16, v125
	v_lshlrev_b32_e32 v178, 16, v141
	v_lshlrev_b32_e32 v179, 16, v93
	v_mul_f32_e32 v184, 0xbfb8aa3b, v176
	v_mul_f32_e32 v185, 0xbfb8aa3b, v177
	v_mul_f32_e32 v186, 0xbfb8aa3b, v178
	v_exp_f32_e32 v184, v184
	v_exp_f32_e32 v185, v185
	v_exp_f32_e32 v186, v186
	v_mul_f32_e32 v179, v179, v227
	v_add_f32_e32 v184, 1.0, v184
	v_add_f32_e32 v185, 1.0, v185
	v_add_f32_e32 v186, 1.0, v186
	v_rcp_f32_e32 v184, v184
	v_rcp_f32_e32 v185, v185
	v_rcp_f32_e32 v186, v186
	v_mul_f32_e32 v179, v179, v58
	v_mul_f32_e32 v176, v176, v184
	v_mul_f32_e32 v178, v26, v226
	v_mul_f32_e32 v179, v179, v176
	v_mul_f32_e32 v178, v178, v170
	v_mul_f32_e32 v179, v179, v185
	v_fmac_f32_e32 v179, v186, v178
	v_and_b32_e32 v180, 0xffff0000, v109
	v_and_b32_e32 v181, 0xffff0000, v125
	v_and_b32_e32 v182, 0xffff0000, v141
	v_and_b32_e32 v183, 0xffff0000, v93
	v_mul_f32_e32 v187, 0xbfb8aa3b, v180
	v_mul_f32_e32 v188, 0xbfb8aa3b, v181
	v_mul_f32_e32 v189, 0xbfb8aa3b, v182
	v_exp_f32_e32 v187, v187
	v_exp_f32_e32 v188, v188
	v_exp_f32_e32 v189, v189
	v_mul_f32_e32 v183, v183, v227
	v_add_f32_e32 v187, 1.0, v187
	v_add_f32_e32 v188, 1.0, v188
	v_add_f32_e32 v189, 1.0, v189
	v_rcp_f32_e32 v187, v187
	v_rcp_f32_e32 v188, v188
	v_rcp_f32_e32 v189, v189
	v_mul_f32_e32 v183, v183, v59
	v_mul_f32_e32 v180, v180, v187
	v_mul_f32_e32 v182, v27, v226
	v_mul_f32_e32 v183, v183, v180
	v_mul_f32_e32 v182, v182, v171
	v_mul_f32_e32 v183, v183, v188
	v_fmac_f32_e32 v183, v189, v182
	v_cvt_pk_bf16_f32 v191, v179, v183
	global_store_dwordx2 v215, v[190:191], s[28:29] offset:192
	s_nop 1
	v_lshlrev_b32_e32 v176, 16, v110
	v_lshlrev_b32_e32 v177, 16, v126
	v_lshlrev_b32_e32 v178, 16, v142
	v_lshlrev_b32_e32 v179, 16, v94
	v_mul_f32_e32 v184, 0xbfb8aa3b, v176
	v_mul_f32_e32 v185, 0xbfb8aa3b, v177
	v_mul_f32_e32 v186, 0xbfb8aa3b, v178
	v_exp_f32_e32 v184, v184
	v_exp_f32_e32 v185, v185
	v_exp_f32_e32 v186, v186
	v_mul_f32_e32 v179, v179, v227
	v_add_f32_e32 v184, 1.0, v184
	v_add_f32_e32 v185, 1.0, v185
	v_add_f32_e32 v186, 1.0, v186
	v_rcp_f32_e32 v184, v184
	v_rcp_f32_e32 v185, v185
	v_rcp_f32_e32 v186, v186
	v_mul_f32_e32 v179, v179, v60
	v_mul_f32_e32 v176, v176, v184
	v_mul_f32_e32 v178, v28, v226
	v_mul_f32_e32 v179, v179, v176
	v_mul_f32_e32 v178, v178, v172
	v_mul_f32_e32 v179, v179, v185
	v_fmac_f32_e32 v179, v186, v178
	v_and_b32_e32 v180, 0xffff0000, v110
	v_and_b32_e32 v181, 0xffff0000, v126
	v_and_b32_e32 v182, 0xffff0000, v142
	v_and_b32_e32 v183, 0xffff0000, v94
	v_mul_f32_e32 v187, 0xbfb8aa3b, v180
	v_mul_f32_e32 v188, 0xbfb8aa3b, v181
	v_mul_f32_e32 v189, 0xbfb8aa3b, v182
	v_exp_f32_e32 v187, v187
	v_exp_f32_e32 v188, v188
	v_exp_f32_e32 v189, v189
	v_mul_f32_e32 v183, v183, v227
	v_add_f32_e32 v187, 1.0, v187
	v_add_f32_e32 v188, 1.0, v188
	v_add_f32_e32 v189, 1.0, v189
	v_rcp_f32_e32 v187, v187
	v_rcp_f32_e32 v188, v188
	v_rcp_f32_e32 v189, v189
	v_mul_f32_e32 v183, v183, v61
	v_mul_f32_e32 v180, v180, v187
	v_mul_f32_e32 v182, v29, v226
	v_mul_f32_e32 v183, v183, v180
	v_mul_f32_e32 v182, v182, v173
	v_mul_f32_e32 v183, v183, v188
	v_fmac_f32_e32 v183, v189, v182
	v_cvt_pk_bf16_f32 v190, v179, v183
	v_lshlrev_b32_e32 v176, 16, v111
	v_lshlrev_b32_e32 v177, 16, v127
	v_lshlrev_b32_e32 v178, 16, v143
	v_lshlrev_b32_e32 v179, 16, v95
	v_mul_f32_e32 v184, 0xbfb8aa3b, v176
	v_mul_f32_e32 v185, 0xbfb8aa3b, v177
	v_mul_f32_e32 v186, 0xbfb8aa3b, v178
	v_exp_f32_e32 v184, v184
	v_exp_f32_e32 v185, v185
	v_exp_f32_e32 v186, v186
	v_mul_f32_e32 v179, v179, v227
	v_add_f32_e32 v184, 1.0, v184
	v_add_f32_e32 v185, 1.0, v185
	v_add_f32_e32 v186, 1.0, v186
	v_rcp_f32_e32 v184, v184
	v_rcp_f32_e32 v185, v185
	v_rcp_f32_e32 v186, v186
	v_mul_f32_e32 v179, v179, v62
	v_mul_f32_e32 v176, v176, v184
	v_mul_f32_e32 v178, v30, v226
	v_mul_f32_e32 v179, v179, v176
	v_mul_f32_e32 v178, v178, v174
	v_mul_f32_e32 v179, v179, v185
	v_fmac_f32_e32 v179, v186, v178
	v_and_b32_e32 v180, 0xffff0000, v111
	v_and_b32_e32 v181, 0xffff0000, v127
	v_and_b32_e32 v182, 0xffff0000, v143
	v_and_b32_e32 v183, 0xffff0000, v95
	v_mul_f32_e32 v187, 0xbfb8aa3b, v180
	v_mul_f32_e32 v188, 0xbfb8aa3b, v181
	v_mul_f32_e32 v189, 0xbfb8aa3b, v182
	v_exp_f32_e32 v187, v187
	v_exp_f32_e32 v188, v188
	v_exp_f32_e32 v189, v189
	v_mul_f32_e32 v183, v183, v227
	v_add_f32_e32 v187, 1.0, v187
	v_add_f32_e32 v188, 1.0, v188
	v_add_f32_e32 v189, 1.0, v189
	v_rcp_f32_e32 v187, v187
	v_rcp_f32_e32 v188, v188
	v_rcp_f32_e32 v189, v189
	v_mul_f32_e32 v183, v183, v63
	v_mul_f32_e32 v180, v180, v187
	v_mul_f32_e32 v182, v31, v226
	v_mul_f32_e32 v183, v183, v180
	v_mul_f32_e32 v182, v182, v175
	v_mul_f32_e32 v183, v183, v188
	v_fmac_f32_e32 v183, v189, v182
	v_cvt_pk_bf16_f32 v191, v179, v183
	global_store_dwordx2 v215, v[190:191], s[28:29] offset:224
	s_nop 1
	s_add_i32 s22, s22, 1
	s_sub_i32 s36, 15, s36
	s_cmp_lt_u32 s22, 2
	s_cbranch_scc1 .Lattn_unit
	s_add_i32 s21, s21, s78
	s_cmpk_lt_i32 s21, 0x200
	s_cbranch_scc1 .Lattn_ploop
	s_branch .LBB0_812

	.amdhsa_kernel _Z10fwd_kernel4Args
		.amdhsa_group_segment_fixed_size 0
		.amdhsa_private_segment_fixed_size 0
		.amdhsa_kernarg_size 432
		.amdhsa_user_sgpr_count 2
		.amdhsa_user_sgpr_dispatch_ptr 0
		.amdhsa_user_sgpr_queue_ptr 0
		.amdhsa_user_sgpr_kernarg_segment_ptr 1
		.amdhsa_user_sgpr_dispatch_id 0
		.amdhsa_user_sgpr_kernarg_preload_length 0
		.amdhsa_user_sgpr_kernarg_preload_offset 0
		.amdhsa_user_sgpr_private_segment_size 0
		.amdhsa_uses_dynamic_stack 0
		.amdhsa_enable_private_segment 0
		.amdhsa_system_sgpr_workgroup_id_x 1
		.amdhsa_system_sgpr_workgroup_id_y 0
		.amdhsa_system_sgpr_workgroup_id_z 0
		.amdhsa_system_sgpr_workgroup_info 0
		.amdhsa_system_vgpr_workitem_id 2
		.amdhsa_next_free_vgpr 256
		.amdhsa_next_free_sgpr 98
		.amdhsa_accum_offset 256
		.amdhsa_reserve_vcc 1
		.amdhsa_float_round_mode_32 0
		.amdhsa_float_round_mode_16_64 0
		.amdhsa_float_denorm_mode_32 3
		.amdhsa_float_denorm_mode_16_64 3
		.amdhsa_dx10_clamp 1
		.amdhsa_ieee_mode 1
		.amdhsa_fp16_overflow 0
		.amdhsa_tg_split 0
		.amdhsa_exception_fp_ieee_invalid_op 0
		.amdhsa_exception_fp_denorm_src 0
		.amdhsa_exception_fp_ieee_div_zero 0
		.amdhsa_exception_fp_ieee_overflow 0
		.amdhsa_exception_fp_ieee_underflow 0
		.amdhsa_exception_fp_ieee_inexact 0
		.amdhsa_exception_int_div_zero 0
	.end_amdhsa_kernel

amdhsa.kernels:
  - .agpr_count:     0
    .args:
      - .offset:         0
        .size:           176
        .value_kind:     by_value
      - .offset:         176
        .size:           4
        .value_kind:     hidden_block_count_x
      - .offset:         180
        .size:           4
        .value_kind:     hidden_block_count_y
      - .offset:         184
        .size:           4
        .value_kind:     hidden_block_count_z
      - .offset:         188
        .size:           2
        .value_kind:     hidden_group_size_x
      - .offset:         190
        .size:           2
        .value_kind:     hidden_group_size_y
      - .offset:         192
        .size:           2
        .value_kind:     hidden_group_size_z
      - .offset:         194
        .size:           2
        .value_kind:     hidden_remainder_x
      - .offset:         196
        .size:           2
        .value_kind:     hidden_remainder_y
      - .offset:         198
        .size:           2
        .value_kind:     hidden_remainder_z
      - .offset:         216
        .size:           8
        .value_kind:     hidden_global_offset_x
      - .offset:         224
        .size:           8
        .value_kind:     hidden_global_offset_y
      - .offset:         232
        .size:           8
        .value_kind:     hidden_global_offset_z
      - .offset:         240
        .size:           2
        .value_kind:     hidden_grid_dims
      - .offset:         264
        .size:           8
        .value_kind:     hidden_multigrid_sync_arg
      - .offset:         296
        .size:           4
        .value_kind:     hidden_dynamic_lds_size
    .group_segment_fixed_size: 0
    .kernarg_segment_align: 8
    .kernarg_segment_size: 432
    .language:       OpenCL C
    .language_version:
      - 2
      - 0
    .max_flat_workgroup_size: 512
    .name:           _Z10fwd_kernel4Args
    .private_segment_fixed_size: 0
    .sgpr_count:     104
    .sgpr_spill_count: 93
    .symbol:         _Z10fwd_kernel4Args.kd
    .uniform_work_group_size: 1
    .uses_dynamic_stack: false
    .vgpr_count:     256
    .vgpr_spill_count: 0
    .wavefront_size: 64
